# scan_c loop: LDS fragments read through a 7-quad ring several MFMAs ahead, next chunk operands fetched by LDS-DMA into idle LDS half and copied after the barrier; nop padding keeps later code alignmen
# baseline (speedup 1.0000x reference)
; #define MFMA32(a, b, c) __builtin_amdgcn_mfma_f32_32x32x16_bf16((a), (b), (c), 0, 0, 0)
; DI void phase_scan_c(int wv_, int vb_, int nvb_, char* ws_, const Ctx& p, char* smem, int half) {
;     ...
;     for (int nc = 0; nc < 32; ++nc) {
;       const size_t uix = (size_t)blk * 32 + nc;
;       const float egl = GL[uix];
;       bf16x8 ucur[4];
; #pragma unroll
;       for (int tb = 0; tb < 2; ++tb) { ucur[2 * tb] = *(const bf16x8*)(CU + (uix * 128 + dv0 + c) * 64 + h * 16 + tb * 32); ucur[2 * tb + 1] = *(const bf16x8*)(CU + (uix * 128 + dv0 + c) * 64 + h * 16 + tb * 32 + 8); }
;       const u16* Wp = sW + c * 136 + h * 8;
;       const u16* Qp = sQ + c * 136 + h * 8;
;       const u16* KTp = sKT + c * 72 + h * 8;
;       const u16* QKp = sQK + c * 72 + h * 8;
;       f32x16 X[2], Oa[2];
;       X[0] = zero16(); X[1] = zero16(); Oa[0] = zero16(); Oa[1] = zero16();
; #pragma unroll
;       for (int mb = 0; mb < 4; ++mb) {
; #pragma unroll
;         for (int s = 0; s < 2; ++s) {
;           const bf16x8 sb = pack8(S[mb], s);
; #pragma unroll
;           for (int tb = 0; tb < 2; ++tb) {
;             bf16x8 a = *(const bf16x8*)(Wp + tb * 32 * 136 + mb * 32 + s * 16);
;             bf16x8 a2 = *(const bf16x8*)(Qp + tb * 32 * 136 + mb * 32 + s * 16);
;             X[tb] = MFMA32(a, sb, X[tb]);
;             Oa[tb] = MFMA32(a2, sb, Oa[tb]);
;           }
;         }
;       }
;     ...
;       { const int ncn = nc < 31 ? nc + 1 : 31; SLOAD((size_t)blk * 32 + ncn) }
.LBB0_232:
	s_add_u32 s12, s4, s16
	s_addc_u32 s13, s5, s17
	v_lshl_add_u64 v[2:3], v[186:187], 0, s[16:17]
	global_load_dword v0, v1, s[12:13]
	global_load_dwordx4 v[144:147], v[2:3], off offset:-64
	global_load_dwordx4 v[10:13], v[2:3], off offset:-48
	global_load_dwordx4 v[6:9], v[2:3], off
	s_nop 0
	global_load_dwordx4 v[2:5], v[2:3], off offset:16
	ds_read_b128 v[84:87], v216 offset:17408
	ds_read_b128 v[88:91], v216
	ds_read_b128 v[148:151], v216 offset:32
	v_cvt_pk_bf16_f32 v80, v16, v17
	v_cvt_pk_bf16_f32 v81, v18, v19
	v_cvt_pk_bf16_f32 v82, v20, v21
	v_cvt_pk_bf16_f32 v83, v22, v23
	v_cvt_pk_bf16_f32 v152, v24, v25
	v_cvt_pk_bf16_f32 v153, v26, v27
	s_waitcnt lgkmcnt(1)
	v_mfma_f32_32x32x16_bf16 v[128:143], v[88:91], v[80:83], 0
	v_cvt_pk_bf16_f32 v154, v28, v29
	v_cvt_pk_bf16_f32 v155, v30, v31
	v_add_co_u32_e64 v218, s[12:13], s1, 1
	s_add_i32 s1, s1, 33
	s_and_b64 s[12:13], s[12:13], exec
	s_cselect_b32 s1, 31, s1
	v_mfma_f32_32x32x16_bf16 v[96:111], v[84:87], v[80:83], 0
	ds_read_b128 v[84:87], v216 offset:8704
	ds_read_b128 v[88:91], v216 offset:26112
	ds_read_b128 v[156:159], v216 offset:17440
	s_add_u32 s12, s56, s1
	s_addc_u32 s13, s57, 0
	s_lshl_b64 s[18:19], s[12:13], 13
	s_lshl_b64 s[12:13], s[12:13], 14
	s_add_u32 s34, s6, s12
	s_waitcnt lgkmcnt(2)
	v_mfma_f32_32x32x16_bf16 v[112:127], v[84:87], v[80:83], 0
	s_addc_u32 s35, s7, s13
	s_add_u32 s44, s8, s12
	s_addc_u32 s45, s9, s13
	s_add_u32 s12, s10, s12
	s_addc_u32 s13, s11, s13
	s_lshl_b32 s98, s33, 10
	s_add_i32 s98, s98, 0x12c00
	s_add_u32 s100, s14, s18
	s_addc_u32 s101, s15, s19
	v_lshl_add_u64 v[160:161], s[12:13], 0, v[200:201]
	v_readfirstlane_b32 s0, v218
	s_waitcnt lgkmcnt(1)
	v_mfma_f32_32x32x16_bf16 v[80:95], v[88:91], v[80:83], 0
	v_lshl_add_u64 v[186:187], v[186:187], 0, s[2:3]
	s_mov_b32 s1, s0
	s_waitcnt vmcnt(4)
	v_mul_f32_e64 v30, v30, v0
	v_mul_f32_e64 v31, v31, v0
	v_mfma_f32_32x32x16_bf16 v[128:143], v[148:151], v[152:155], v[128:143]
	s_mov_b32 m0, s98
	s_nop 0
	global_load_lds_dwordx4 v188, s[34:35]
	v_mul_f32_e64 v28, v28, v0
	v_mul_f32_e64 v29, v29, v0
	v_mul_f32_e64 v26, v26, v0
	v_mul_f32_e64 v27, v27, v0
	v_mul_f32_e64 v24, v24, v0
	v_mul_f32_e64 v25, v25, v0
	v_pk_mul_f32 v[22:23], v[22:23], v[0:1] op_sel_hi:[1,0]
	v_pk_mul_f32 v[20:21], v[20:21], v[0:1] op_sel_hi:[1,0]
	v_pk_mul_f32 v[18:19], v[18:19], v[0:1] op_sel_hi:[1,0]
	v_pk_mul_f32 v[16:17], v[16:17], v[0:1] op_sel_hi:[1,0]
	s_waitcnt lgkmcnt(0)
	v_mfma_f32_32x32x16_bf16 v[96:111], v[156:159], v[152:155], v[96:111]
	s_add_i32 m0, s98, 0x1000
	s_nop 0
	global_load_lds_dwordx4 v190, s[34:35]
	ds_read_b128 v[148:151], v216 offset:8736
	ds_read_b128 v[156:159], v216 offset:26144
	s_waitcnt lgkmcnt(1)
	v_mfma_f32_32x32x16_bf16 v[112:127], v[148:151], v[152:155], v[112:127]
	s_add_i32 m0, s98, 0x2000
	s_nop 0
	global_load_lds_dwordx4 v192, s[34:35]
	v_cvt_pk_bf16_f32 v148, v32, v33
	v_cvt_pk_bf16_f32 v149, v34, v35
	v_cvt_pk_bf16_f32 v150, v36, v37
	v_cvt_pk_bf16_f32 v151, v38, v39
	v_mul_f32_e64 v38, v38, v0
	v_mul_f32_e64 v39, v39, v0
	v_pk_mul_f32 v[36:37], v[36:37], v[0:1] op_sel_hi:[1,0]
	v_pk_mul_f32 v[34:35], v[34:35], v[0:1] op_sel_hi:[1,0]
	s_waitcnt lgkmcnt(0)
	v_mfma_f32_32x32x16_bf16 v[80:95], v[156:159], v[152:155], v[80:95]
	s_add_i32 m0, s98, 0x3000
	s_nop 0
	global_load_lds_dwordx4 v200, s[34:35]
	ds_read_b128 v[228:231], v216 offset:64
	ds_read_b128 v[232:235], v216 offset:17472
	ds_read_b128 v[236:239], v216 offset:8768
	ds_read_b128 v[246:249], v216 offset:26176
	ds_read_b128 v[194:197], v216 offset:96
	ds_read_b128 v[220:223], v216 offset:17504
	v_mul_f32_e64 v32, v32, v0
	v_mul_f32_e64 v33, v33, v0
	s_waitcnt lgkmcnt(5)
	v_mfma_f32_32x32x16_bf16 v[128:143], v[228:231], v[148:151], v[128:143]
	s_add_i32 m0, s98, 0x4000
	s_nop 0
	global_load_lds_dwordx4 v188, s[44:45]
	ds_read_b128 v[224:227], v216 offset:8800
	s_waitcnt lgkmcnt(5)
	v_mfma_f32_32x32x16_bf16 v[96:111], v[232:235], v[148:151], v[96:111]
	s_add_i32 m0, s98, 0x5000
	s_nop 0
	global_load_lds_dwordx4 v190, s[44:45]
	ds_read_b128 v[228:231], v216 offset:26208
	s_waitcnt lgkmcnt(5)
	v_mfma_f32_32x32x16_bf16 v[112:127], v[236:239], v[148:151], v[112:127]
	s_add_i32 m0, s98, 0x6000
	s_nop 0
	global_load_lds_dwordx4 v192, s[44:45]
	ds_read_b128 v[232:235], v216 offset:128
	s_waitcnt lgkmcnt(5)
	v_mfma_f32_32x32x16_bf16 v[80:95], v[246:249], v[148:151], v[80:95]
	s_add_i32 m0, s98, 0x7000
	s_nop 0
	global_load_lds_dwordx4 v200, s[44:45]
	ds_read_b128 v[236:239], v216 offset:17536
	v_cvt_pk_bf16_f32 v148, v40, v41
	v_cvt_pk_bf16_f32 v149, v42, v43
	v_cvt_pk_bf16_f32 v150, v44, v45
	v_cvt_pk_bf16_f32 v151, v46, v47
	v_pk_mul_f32 v[46:47], v[46:47], v[0:1] op_sel_hi:[1,0]
	v_pk_mul_f32 v[44:45], v[44:45], v[0:1] op_sel_hi:[1,0]
	s_waitcnt lgkmcnt(5)
	v_mfma_f32_32x32x16_bf16 v[128:143], v[194:197], v[148:151], v[128:143]
	s_add_i32 m0, s98, 0x8000
	s_nop 0
	global_load_lds_dwordx4 v188, s[12:13]
	ds_read_b128 v[246:249], v216 offset:8832
	v_mul_f32_e64 v42, v42, v0
	v_mul_f32_e64 v43, v43, v0
	v_mul_f32_e64 v40, v40, v0
	v_mul_f32_e64 v41, v41, v0
	s_waitcnt lgkmcnt(5)
	v_mfma_f32_32x32x16_bf16 v[96:111], v[220:223], v[148:151], v[96:111]
	s_add_i32 m0, s98, 0x9000
	s_nop 0
	global_load_lds_dwordx4 v190, s[12:13]
	ds_read_b128 v[194:197], v216 offset:26240
	s_waitcnt lgkmcnt(5)
	v_mfma_f32_32x32x16_bf16 v[112:127], v[224:227], v[148:151], v[112:127]
	s_add_i32 m0, s98, 0xa000
	s_nop 0
	global_load_lds_dwordx4 v192, s[12:13]
	ds_read_b128 v[220:223], v216 offset:160
	s_waitcnt lgkmcnt(5)
; #define MFMA32(a, b, c) __builtin_amdgcn_mfma_f32_32x32x16_bf16((a), (b), (c), 0, 0, 0)
; DI float bfs(short v) { return __uint_as_float(((unsigned)(u16)v) << 16); }
; DI void phase_scan_c(int wv_, int vb_, int nvb_, char* ws_, const Ctx& p, char* smem, int half) {
;     ...
; #pragma unroll
;       for (int mb = 0; mb < 4; ++mb) {
; #pragma unroll
;         for (int s = 0; s < 2; ++s) {
;           const bf16x8 sb = pack8(S[mb], s);
; #pragma unroll
;           for (int tb = 0; tb < 2; ++tb) {
;             bf16x8 a = *(const bf16x8*)(Wp + tb * 32 * 136 + mb * 32 + s * 16);
;             bf16x8 a2 = *(const bf16x8*)(Qp + tb * 32 * 136 + mb * 32 + s * 16);
;             X[tb] = MFMA32(a, sb, X[tb]);
;             Oa[tb] = MFMA32(a2, sb, Oa[tb]);
;           }
;         }
;       }
;       bf16x8 vb[2][2];
; #pragma unroll
;       for (int tb = 0; tb < 2; ++tb) {
; #pragma unroll
;         for (int i = 0; i < 8; ++i) { X[tb][i] = bfs(ucur[2 * tb][i]) - X[tb][i]; X[tb][8 + i] = bfs(ucur[2 * tb + 1][i]) - X[tb][8 + i]; }
;         vb[tb][0] = pack8(X[tb], 0); vb[tb][1] = pack8(X[tb], 1);
;       }
;       { const int ncn = nc < 31 ? nc + 1 : 31; SLOAD((size_t)blk * 32 + ncn) }
; #pragma unroll
;       for (int tb = 0; tb < 2; ++tb)
; #pragma unroll
;         for (int tb2 = 0; tb2 < 2; ++tb2)
; #pragma unroll
;           for (int s = 0; s < 2; ++s) {
;             bf16x8 a = *(const bf16x8*)(QKp + tb * 32 * 72 + tb2 * 32 + s * 16);
;             Oa[tb] = MFMA32(a, vb[tb2][s], Oa[tb]);
;           }
	v_mfma_f32_32x32x16_bf16 v[80:95], v[228:231], v[148:151], v[80:95]
	s_add_i32 m0, s98, 0xb000
	s_nop 0
	global_load_lds_dwordx4 v200, s[12:13]
	ds_read_b128 v[224:227], v216 offset:17568
	v_cvt_pk_bf16_f32 v148, v48, v49
	v_cvt_pk_bf16_f32 v149, v50, v51
	v_cvt_pk_bf16_f32 v150, v52, v53
	v_cvt_pk_bf16_f32 v151, v54, v55
	v_pk_mul_f32 v[54:55], v[54:55], v[0:1] op_sel_hi:[1,0]
	v_pk_mul_f32 v[52:53], v[52:53], v[0:1] op_sel_hi:[1,0]
	s_waitcnt lgkmcnt(5)
	v_mfma_f32_32x32x16_bf16 v[128:143], v[232:235], v[148:151], v[128:143]
	s_add_i32 m0, s98, 0xc000
	s_nop 0
	global_load_lds_dwordx4 v14, s[100:101]
	ds_read_b128 v[228:231], v216 offset:8864
	v_mul_f32_e64 v50, v50, v0
	v_mul_f32_e64 v51, v51, v0
	v_mul_f32_e64 v48, v48, v0
	v_mul_f32_e64 v49, v49, v0
	s_waitcnt lgkmcnt(5)
	v_mfma_f32_32x32x16_bf16 v[96:111], v[236:239], v[148:151], v[96:111]
	s_add_i32 m0, s98, 0xd000
	s_nop 0
	global_load_lds_dwordx4 v174, s[100:101]
	ds_read_b128 v[232:235], v216 offset:26272
	s_waitcnt lgkmcnt(5)
	v_mfma_f32_32x32x16_bf16 v[112:127], v[246:249], v[148:151], v[112:127]
	ds_read_b128 v[236:239], v216 offset:192
	s_waitcnt lgkmcnt(5)
	v_mfma_f32_32x32x16_bf16 v[80:95], v[194:197], v[148:151], v[80:95]
	ds_read_b128 v[246:249], v216 offset:17600
	v_cvt_pk_bf16_f32 v148, v56, v57
	v_cvt_pk_bf16_f32 v149, v58, v59
	v_cvt_pk_bf16_f32 v150, v60, v61
	v_cvt_pk_bf16_f32 v151, v62, v63
	v_pk_mul_f32 v[62:63], v[62:63], v[0:1] op_sel_hi:[1,0]
	v_pk_mul_f32 v[60:61], v[60:61], v[0:1] op_sel_hi:[1,0]
	s_waitcnt lgkmcnt(5)
	v_mfma_f32_32x32x16_bf16 v[128:143], v[220:223], v[148:151], v[128:143]
	ds_read_b128 v[194:197], v216 offset:8896
	v_mul_f32_e64 v58, v58, v0
	v_mul_f32_e64 v59, v59, v0
	v_mul_f32_e64 v56, v56, v0
	v_mul_f32_e64 v57, v57, v0
	s_waitcnt lgkmcnt(5)
	v_mfma_f32_32x32x16_bf16 v[96:111], v[224:227], v[148:151], v[96:111]
	ds_read_b128 v[220:223], v216 offset:26304
	s_waitcnt lgkmcnt(5)
	v_mfma_f32_32x32x16_bf16 v[112:127], v[228:231], v[148:151], v[112:127]
	ds_read_b128 v[224:227], v216 offset:224
	s_waitcnt lgkmcnt(5)
	v_mfma_f32_32x32x16_bf16 v[80:95], v[232:235], v[148:151], v[80:95]
	ds_read_b128 v[228:231], v216 offset:17632
	v_cvt_pk_bf16_f32 v148, v64, v65
	v_cvt_pk_bf16_f32 v149, v66, v67
	v_cvt_pk_bf16_f32 v150, v68, v69
	v_cvt_pk_bf16_f32 v151, v70, v71
	v_pk_mul_f32 v[70:71], v[70:71], v[0:1] op_sel_hi:[1,0]
	v_pk_mul_f32 v[68:69], v[68:69], v[0:1] op_sel_hi:[1,0]
	s_waitcnt lgkmcnt(5)
	v_mfma_f32_32x32x16_bf16 v[128:143], v[236:239], v[148:151], v[128:143]
	ds_read_b128 v[232:235], v216 offset:8928
	v_mul_f32_e64 v66, v66, v0
	v_mul_f32_e64 v67, v67, v0
	v_mul_f32_e64 v64, v64, v0
	v_mul_f32_e64 v65, v65, v0
	s_waitcnt lgkmcnt(5)
	v_mfma_f32_32x32x16_bf16 v[96:111], v[246:249], v[148:151], v[96:111]
	ds_read_b128 v[236:239], v216 offset:26336
	s_waitcnt lgkmcnt(5)
	v_mfma_f32_32x32x16_bf16 v[112:127], v[194:197], v[148:151], v[112:127]
	ds_read_b128 v[246:249], v217 offset:53248
	s_waitcnt lgkmcnt(5)
	v_mfma_f32_32x32x16_bf16 v[80:95], v[220:223], v[148:151], v[80:95]
	ds_read_b128 v[194:197], v217 offset:53280
	v_cvt_pk_bf16_f32 v148, v72, v73
	v_cvt_pk_bf16_f32 v149, v74, v75
	v_cvt_pk_bf16_f32 v150, v76, v77
	v_cvt_pk_bf16_f32 v151, v78, v79
	v_pk_mul_f32 v[78:79], v[78:79], v[0:1] op_sel_hi:[1,0]
	v_pk_mul_f32 v[76:77], v[76:77], v[0:1] op_sel_hi:[1,0]
	s_waitcnt lgkmcnt(5)
	v_mfma_f32_32x32x16_bf16 v[128:143], v[224:227], v[148:151], v[128:143]
	ds_read_b128 v[220:223], v217 offset:53312
	v_mul_f32_e64 v74, v74, v0
	v_mul_f32_e64 v75, v75, v0
	v_mul_f32_e64 v72, v72, v0
	v_mul_f32_e64 v73, v73, v0
	s_waitcnt lgkmcnt(5)
	v_mfma_f32_32x32x16_bf16 v[96:111], v[228:231], v[148:151], v[96:111]
	ds_read_b128 v[224:227], v217 offset:53344
	s_nop 0
	s_waitcnt lgkmcnt(5)
	v_mfma_f32_32x32x16_bf16 v[112:127], v[232:235], v[148:151], v[112:127]
	ds_read_b128 v[228:231], v217 offset:57856
	v_lshl_add_u64 v[152:153], s[34:35], 0, v[200:201]
	s_nop 0
	s_waitcnt lgkmcnt(5)
	v_mfma_f32_32x32x16_bf16 v[80:95], v[236:239], v[148:151], v[80:95]
	ds_read_b128 v[232:235], v217 offset:57888
	s_waitcnt vmcnt(17)
	v_and_b32_e32 v149, 0xffff0000, v144
	v_lshlrev_b32_e32 v148, 16, v144
	v_add_f32_e64 v128, v148, -v128
	v_add_f32_e64 v129, v149, -v129
	s_waitcnt vmcnt(16)
	v_and_b32_e32 v149, 0xffff0000, v10
	v_lshlrev_b32_e32 v148, 16, v10
	v_pk_add_f32 v[136:137], v[148:149], v[136:137] neg_lo:[0,1] neg_hi:[0,1]
	v_and_b32_e32 v149, 0xffff0000, v145
	v_lshlrev_b32_e32 v148, 16, v145
	v_and_b32_e32 v145, 0xffff0000, v11
	v_lshlrev_b32_e32 v144, 16, v11
	v_and_b32_e32 v11, 0xffff0000, v146
	v_lshlrev_b32_e32 v10, 16, v146
	v_pk_add_f32 v[10:11], v[10:11], v[132:133] neg_lo:[0,1] neg_hi:[0,1]
	v_and_b32_e32 v133, 0xffff0000, v12
	v_lshlrev_b32_e32 v132, 16, v12
	v_pk_add_f32 v[132:133], v[132:133], v[140:141] neg_lo:[0,1] neg_hi:[0,1]
	v_and_b32_e32 v141, 0xffff0000, v147
	v_lshlrev_b32_e32 v140, 16, v147
	v_pk_add_f32 v[130:131], v[148:149], v[130:131] neg_lo:[0,1] neg_hi:[0,1]
	v_pk_add_f32 v[134:135], v[140:141], v[134:135] neg_lo:[0,1] neg_hi:[0,1]
	v_cvt_pk_bf16_f32 v128, v128, v129
	v_cvt_pk_bf16_f32 v129, v130, v131
	v_cvt_pk_bf16_f32 v130, v10, v11
	v_cvt_pk_bf16_f32 v131, v134, v135
	v_and_b32_e32 v141, 0xffff0000, v13
	v_lshlrev_b32_e32 v140, 16, v13
	s_waitcnt lgkmcnt(5)
	v_mfma_f32_32x32x16_bf16 v[96:111], v[246:249], v[128:131], v[96:111]
	ds_read_b128 v[236:239], v217 offset:57920
	v_add_f32_e64 v138, v144, -v138
	v_add_f32_e64 v139, v145, -v139
	v_add_f32_e64 v140, v140, -v142
	v_add_f32_e64 v141, v141, -v143
	v_cvt_pk_bf16_f32 v10, v136, v137
	v_cvt_pk_bf16_f32 v11, v138, v139
	v_cvt_pk_bf16_f32 v12, v132, v133
	v_cvt_pk_bf16_f32 v13, v140, v141
	s_waitcnt vmcnt(15)
; #define MFMA32(a, b, c) __builtin_amdgcn_mfma_f32_32x32x16_bf16((a), (b), (c), 0, 0, 0)
; DI void phase_scan_c(int wv_, int vb_, int nvb_, char* ws_, const Ctx& p, char* smem, int half) {
;     ...
; #pragma unroll
;       for (int tb = 0; tb < 2; ++tb)
; #pragma unroll
;         for (int tb2 = 0; tb2 < 2; ++tb2)
; #pragma unroll
;           for (int s = 0; s < 2; ++s) {
;             bf16x8 a = *(const bf16x8*)(QKp + tb * 32 * 72 + tb2 * 32 + s * 16);
;             Oa[tb] = MFMA32(a, vb[tb2][s], Oa[tb]);
;           }
; #pragma unroll
;       for (int mb = 0; mb < 4; ++mb) {
; #pragma unroll
;         for (int i = 0; i < 16; ++i) S[mb][i] *= egl;
; #pragma unroll
;         for (int tb = 0; tb < 2; ++tb)
; #pragma unroll
;           for (int s = 0; s < 2; ++s) {
;             bf16x8 a = *(const bf16x8*)(KTp + mb * 32 * 72 + tb * 32 + s * 16);
;             S[mb] = MFMA32(a, vb[tb][s], S[mb]);
;           }
;       }
	v_and_b32_e32 v133, 0xffff0000, v6
	v_lshlrev_b32_e32 v132, 16, v6
	s_waitcnt lgkmcnt(5)
	v_mfma_f32_32x32x16_bf16 v[96:111], v[194:197], v[10:13], v[96:111]
	ds_read_b128 v[246:249], v217 offset:57952
	v_add_f32_e64 v112, v132, -v112
	v_add_f32_e64 v113, v133, -v113
	s_waitcnt vmcnt(14)
	v_and_b32_e32 v133, 0xffff0000, v2
	v_lshlrev_b32_e32 v132, 16, v2
	v_pk_add_f32 v[120:121], v[132:133], v[120:121] neg_lo:[0,1] neg_hi:[0,1]
	v_and_b32_e32 v133, 0xffff0000, v7
	v_lshlrev_b32_e32 v132, 16, v7
	v_and_b32_e32 v7, 0xffff0000, v3
	v_lshlrev_b32_e32 v6, 16, v3
	v_pk_add_f32 v[122:123], v[6:7], v[122:123] neg_lo:[0,1] neg_hi:[0,1]
	v_and_b32_e32 v3, 0xffff0000, v8
	v_lshlrev_b32_e32 v2, 16, v8
	v_and_b32_e32 v7, 0xffff0000, v4
	v_lshlrev_b32_e32 v6, 16, v4
	v_pk_add_f32 v[2:3], v[2:3], v[116:117] neg_lo:[0,1] neg_hi:[0,1]
	v_pk_add_f32 v[116:117], v[6:7], v[124:125] neg_lo:[0,1] neg_hi:[0,1]
	v_and_b32_e32 v7, 0xffff0000, v9
	v_lshlrev_b32_e32 v6, 16, v9
	v_pk_add_f32 v[114:115], v[132:133], v[114:115] neg_lo:[0,1] neg_hi:[0,1]
	v_pk_add_f32 v[118:119], v[6:7], v[118:119] neg_lo:[0,1] neg_hi:[0,1]
	v_and_b32_e32 v7, 0xffff0000, v5
	v_lshlrev_b32_e32 v6, 16, v5
	v_pk_add_f32 v[124:125], v[6:7], v[126:127] neg_lo:[0,1] neg_hi:[0,1]
	v_cvt_pk_bf16_f32 v6, v112, v113
	v_cvt_pk_bf16_f32 v7, v114, v115
	v_cvt_pk_bf16_f32 v8, v2, v3
	v_cvt_pk_bf16_f32 v9, v118, v119
	v_cvt_pk_bf16_f32 v2, v120, v121
	v_cvt_pk_bf16_f32 v3, v122, v123
	s_waitcnt lgkmcnt(5)
	v_mfma_f32_32x32x16_bf16 v[96:111], v[220:223], v[6:9], v[96:111]
	ds_read_b128 v[194:197], v217 offset:34816
	v_cvt_pk_bf16_f32 v4, v116, v117
	v_cvt_pk_bf16_f32 v5, v124, v125
	v_lshl_add_u64 v[120:121], s[12:13], 0, v[188:189]
	v_lshl_add_u64 v[136:137], s[12:13], 0, v[190:191]
	v_lshl_add_u64 v[148:149], s[12:13], 0, v[192:193]
	s_add_u32 s12, s14, s18
	s_waitcnt lgkmcnt(5)
	v_mfma_f32_32x32x16_bf16 v[96:111], v[224:227], v[2:5], v[96:111]
	ds_read_b128 v[220:223], v217 offset:34848
	s_addc_u32 s13, s15, s19
	v_lshl_add_u64 v[112:113], s[34:35], 0, v[188:189]
	v_lshl_add_u64 v[116:117], s[44:45], 0, v[188:189]
	v_lshl_add_u64 v[124:125], s[34:35], 0, v[190:191]
	v_lshl_add_u64 v[132:133], s[44:45], 0, v[190:191]
	v_lshl_add_u64 v[140:141], s[34:35], 0, v[192:193]
	s_waitcnt lgkmcnt(5)
	v_mfma_f32_32x32x16_bf16 v[80:95], v[228:231], v[128:131], v[80:95]
	ds_read_b128 v[224:227], v217 offset:34880
	v_lshl_add_u64 v[144:145], s[44:45], 0, v[192:193]
	v_lshl_add_u64 v[156:157], s[44:45], 0, v[200:201]
	v_lshl_add_u64 v[164:165], s[12:13], 0, v[14:15]
	v_lshl_add_u64 v[168:169], s[12:13], 0, v[174:175]
	s_nop 0
	v_cvt_pk_bf16_f32 v0, v96, s0
	s_waitcnt lgkmcnt(5)
	v_mfma_f32_32x32x16_bf16 v[80:95], v[232:235], v[10:13], v[80:95]
	ds_read_b128 v[228:231], v217 offset:34912
	s_nop 0
	s_add_u32 s4, s4, 4
	s_nop 0
	s_addc_u32 s5, s5, 0
	s_nop 0
	s_waitcnt lgkmcnt(5)
	v_mfma_f32_32x32x16_bf16 v[80:95], v[236:239], v[6:9], v[80:95]
	ds_read_b128 v[232:235], v217 offset:39424
	s_nop 0
	s_nop 0
	s_nop 0
	s_nop 0
	s_nop 0
	s_nop 0
	s_nop 0
	s_waitcnt lgkmcnt(5)
	v_mfma_f32_32x32x16_bf16 v[80:95], v[246:249], v[2:5], v[80:95]
	ds_read_b128 v[236:239], v217 offset:39456
	s_nop 0
	s_nop 0
	s_nop 0
	s_nop 0
	s_nop 0
	s_nop 0
	s_nop 0
	s_waitcnt lgkmcnt(5)
	v_mfma_f32_32x32x16_bf16 v[16:31], v[194:197], v[128:131], v[16:31]
	ds_read_b128 v[246:249], v217 offset:39488
	s_waitcnt lgkmcnt(5)
	v_mfma_f32_32x32x16_bf16 v[16:31], v[220:223], v[10:13], v[16:31]
	ds_read_b128 v[194:197], v217 offset:39520
	s_waitcnt lgkmcnt(5)
	v_mfma_f32_32x32x16_bf16 v[16:31], v[224:227], v[6:9], v[16:31]
	ds_read_b128 v[220:223], v217 offset:44032
	s_waitcnt lgkmcnt(5)
	v_mfma_f32_32x32x16_bf16 v[16:31], v[228:231], v[2:5], v[16:31]
	ds_read_b128 v[224:227], v217 offset:44064
	s_waitcnt lgkmcnt(5)
	v_mfma_f32_32x32x16_bf16 v[32:47], v[232:235], v[128:131], v[32:47]
	ds_read_b128 v[228:231], v217 offset:44096
	s_waitcnt lgkmcnt(5)
	v_mfma_f32_32x32x16_bf16 v[32:47], v[236:239], v[10:13], v[32:47]
	ds_read_b128 v[232:235], v217 offset:44128
	s_waitcnt lgkmcnt(5)
	v_mfma_f32_32x32x16_bf16 v[32:47], v[246:249], v[6:9], v[32:47]
	ds_read_b128 v[236:239], v217 offset:48640
	s_waitcnt lgkmcnt(5)
	v_mfma_f32_32x32x16_bf16 v[32:47], v[194:197], v[2:5], v[32:47]
	ds_read_b128 v[246:249], v217 offset:48672
	s_waitcnt lgkmcnt(5)
	v_mfma_f32_32x32x16_bf16 v[48:63], v[220:223], v[128:131], v[48:63]
	ds_read_b128 v[194:197], v217 offset:48704
	s_waitcnt lgkmcnt(5)
	v_mfma_f32_32x32x16_bf16 v[48:63], v[224:227], v[10:13], v[48:63]
	ds_read_b128 v[220:223], v217 offset:48736
	s_waitcnt lgkmcnt(5)
	v_mfma_f32_32x32x16_bf16 v[48:63], v[228:231], v[6:9], v[48:63]
	s_waitcnt lgkmcnt(4)
	v_mfma_f32_32x32x16_bf16 v[48:63], v[232:235], v[2:5], v[48:63]
	s_waitcnt lgkmcnt(3)
	v_mfma_f32_32x32x16_bf16 v[64:79], v[236:239], v[128:131], v[64:79]
	s_waitcnt lgkmcnt(2)
	v_mfma_f32_32x32x16_bf16 v[64:79], v[246:249], v[10:13], v[64:79]
	s_waitcnt lgkmcnt(1)
	v_mfma_f32_32x32x16_bf16 v[64:79], v[194:197], v[6:9], v[64:79]
	s_waitcnt lgkmcnt(0)
; #define MFMA32(a, b, c) __builtin_amdgcn_mfma_f32_32x32x16_bf16((a), (b), (c), 0, 0, 0)
; DI u16 f2bf(float x) { return (u16)(pk2bf(x, 0.f) & 0xffffu); }
; DI int crow(int i, int h) { return (i & 3) + 8 * (i >> 2) + 4 * h; }
; DI void phase_scan_c(int wv_, int vb_, int nvb_, char* ws_, const Ctx& p, char* smem, int half) {
;     ...
; #pragma unroll
;       for (int mb = 0; mb < 4; ++mb) {
; #pragma unroll
;         for (int i = 0; i < 16; ++i) S[mb][i] *= egl;
; #pragma unroll
;         for (int tb = 0; tb < 2; ++tb)
; #pragma unroll
;           for (int s = 0; s < 2; ++s) {
;             bf16x8 a = *(const bf16x8*)(KTp + mb * 32 * 72 + tb * 32 + s * 16);
;             S[mb] = MFMA32(a, vb[tb][s], S[mb]);
;           }
;       }
;       u16* op = O + ((size_t)b * SEQ + (size_t)(half * 32 + nc) * 64) * 1024 + hd * 128 + dv0 + c;
; #pragma unroll
;       for (int tb = 0; tb < 2; ++tb)
; #pragma unroll
;         for (int i = 0; i < 16; ++i) op[(size_t)(tb * 32 + crow(i, h)) * 1024] = f2bf(Oa[tb][i]);
;       __syncthreads();
	v_mfma_f32_32x32x16_bf16 v[64:79], v[220:223], v[2:5], v[64:79]
	v_lshl_add_u64 v[2:3], v[184:185], 0, s[16:17]
	v_add_co_u32_e32 v4, vcc, s52, v2
	v_lshl_add_u64 v[184:185], v[184:185], 0, s[96:97]
	s_nop 0
	v_addc_co_u32_e32 v5, vcc, 0, v3, vcc
	v_add_co_u32_e32 v6, vcc, s62, v2
	s_nop 1
	v_addc_co_u32_e32 v7, vcc, 0, v3, vcc
	global_store_short v[6:7], v0, off offset:-4096
	v_cvt_pk_bf16_f32 v0, v97, s0
	global_store_short v[4:5], v0, off offset:2048
	v_cvt_pk_bf16_f32 v0, v98, s0
	v_add_co_u32_e32 v4, vcc, s63, v2
	global_store_short v[6:7], v0, off
	v_cvt_pk_bf16_f32 v0, v99, s0
	v_addc_co_u32_e32 v5, vcc, 0, v3, vcc
	global_store_short v[6:7], v0, off offset:2048
	v_add_co_u32_e32 v6, vcc, s64, v2
	v_cvt_pk_bf16_f32 v0, v100, s0
	s_nop 0
	v_addc_co_u32_e32 v7, vcc, 0, v3, vcc
	global_store_short v[6:7], v0, off offset:-4096
	v_cvt_pk_bf16_f32 v0, v101, s0
	global_store_short v[4:5], v0, off offset:2048
	v_cvt_pk_bf16_f32 v0, v102, s0
	v_add_co_u32_e32 v4, vcc, s65, v2
	global_store_short v[6:7], v0, off
	v_cvt_pk_bf16_f32 v0, v103, s0
	v_addc_co_u32_e32 v5, vcc, 0, v3, vcc
	global_store_short v[6:7], v0, off offset:2048
	v_add_co_u32_e32 v6, vcc, s68, v2
	v_cvt_pk_bf16_f32 v0, v104, s0
	s_nop 0
	v_addc_co_u32_e32 v7, vcc, 0, v3, vcc
	global_store_short v[6:7], v0, off offset:-4096
	v_cvt_pk_bf16_f32 v0, v105, s0
	global_store_short v[4:5], v0, off offset:2048
	v_cvt_pk_bf16_f32 v0, v106, s0
	v_add_co_u32_e32 v4, vcc, s69, v2
	global_store_short v[6:7], v0, off
	v_cvt_pk_bf16_f32 v0, v107, s0
	v_addc_co_u32_e32 v5, vcc, 0, v3, vcc
	global_store_short v[6:7], v0, off offset:2048
	v_add_co_u32_e32 v6, vcc, s72, v2
	v_cvt_pk_bf16_f32 v0, v108, s0
	s_nop 0
	v_addc_co_u32_e32 v7, vcc, 0, v3, vcc
	global_store_short v[6:7], v0, off offset:-4096
	v_cvt_pk_bf16_f32 v0, v109, s0
	global_store_short v[4:5], v0, off offset:2048
	v_cvt_pk_bf16_f32 v0, v110, s0
	v_add_co_u32_e32 v4, vcc, s73, v2
	global_store_short v[6:7], v0, off
	v_cvt_pk_bf16_f32 v0, v111, s0
	v_addc_co_u32_e32 v5, vcc, 0, v3, vcc
	global_store_short v[6:7], v0, off offset:2048
	v_add_co_u32_e32 v6, vcc, s76, v2
	v_cvt_pk_bf16_f32 v0, v80, s0
	s_nop 0
	v_addc_co_u32_e32 v7, vcc, 0, v3, vcc
	global_store_short v[6:7], v0, off offset:-4096
	v_cvt_pk_bf16_f32 v0, v81, s0
	global_store_short v[4:5], v0, off offset:2048
	v_cvt_pk_bf16_f32 v0, v82, s0
	v_add_co_u32_e32 v4, vcc, s77, v2
	global_store_short v[6:7], v0, off
	v_cvt_pk_bf16_f32 v0, v83, s0
	v_addc_co_u32_e32 v5, vcc, 0, v3, vcc
	global_store_short v[6:7], v0, off offset:2048
	v_add_co_u32_e32 v6, vcc, s88, v2
	v_cvt_pk_bf16_f32 v0, v84, s0
	s_nop 0
	v_addc_co_u32_e32 v7, vcc, 0, v3, vcc
	global_store_short v[6:7], v0, off offset:-4096
	v_cvt_pk_bf16_f32 v0, v85, s0
	global_store_short v[4:5], v0, off offset:2048
	v_cvt_pk_bf16_f32 v0, v86, s0
	v_add_co_u32_e32 v4, vcc, s89, v2
	global_store_short v[6:7], v0, off
	v_cvt_pk_bf16_f32 v0, v87, s0
	v_addc_co_u32_e32 v5, vcc, 0, v3, vcc
	global_store_short v[6:7], v0, off offset:2048
	v_add_co_u32_e32 v6, vcc, s90, v2
	v_cvt_pk_bf16_f32 v0, v88, s0
	s_nop 0
	v_addc_co_u32_e32 v7, vcc, 0, v3, vcc
	global_store_short v[6:7], v0, off offset:-4096
	v_cvt_pk_bf16_f32 v0, v89, s0
	global_store_short v[4:5], v0, off offset:2048
	v_add_co_u32_e32 v4, vcc, s91, v2
	v_cvt_pk_bf16_f32 v0, v90, s0
	s_nop 0
	v_addc_co_u32_e32 v5, vcc, 0, v3, vcc
	global_store_short v[6:7], v0, off
	v_cvt_pk_bf16_f32 v0, v91, s0
	v_add_co_u32_e32 v2, vcc, s94, v2
	global_store_short v[6:7], v0, off offset:2048
	v_cvt_pk_bf16_f32 v0, v92, s0
	v_addc_co_u32_e32 v3, vcc, 0, v3, vcc
	global_store_short v[2:3], v0, off offset:-4096
	v_cvt_pk_bf16_f32 v0, v93, s0
	global_store_short v[4:5], v0, off offset:2048
	v_cvt_pk_bf16_f32 v0, v94, s0
	v_cmp_eq_u32_e32 vcc, 0, v218
	global_store_short v[2:3], v0, off
	v_cvt_pk_bf16_f32 v0, v95, s0
	s_and_b64 vcc, exec, vcc
	global_store_short v[2:3], v0, off offset:2048
	s_waitcnt vmcnt(32)
	s_barrier
; DI void phase_scan_c(int wv_, int vb_, int nvb_, char* ws_, const Ctx& p, char* smem, int half) {
;     ...
;       __syncthreads();
;       SWRITE()
;       __syncthreads();
;     ...
;     if (half == 0) {
; #pragma unroll
;       for (int mb = 0; mb < 4; ++mb)
; #pragma unroll
;         for (int i = 0; i < 16; ++i) stp[(mb * 16 + i) * 64] = S[mb][i];
;     }
	v_add_u32_e32 v198, 0x12c00, v188
	ds_read_b128 v[112:115], v198
	ds_read_b128 v[116:119], v198 offset:16384
	ds_read_b128 v[120:123], v198 offset:32768
	ds_read_b128 v[124:127], v198 offset:4096
	ds_read_b128 v[132:135], v198 offset:20480
	ds_read_b128 v[136:139], v198 offset:36864
	ds_read_b128 v[140:143], v198 offset:8192
	ds_read_b128 v[144:147], v198 offset:24576
	ds_read_b128 v[148:151], v198 offset:40960
	ds_read_b128 v[152:155], v198 offset:12288
	ds_read_b128 v[156:159], v198 offset:28672
	ds_read_b128 v[160:163], v198 offset:45056
	ds_read_b128 v[164:167], v198 offset:49152
	ds_read_b128 v[168:171], v198 offset:53248
	s_waitcnt lgkmcnt(13)
	ds_write_b128 v176, v[112:115]
	s_waitcnt lgkmcnt(13)
	ds_write_b128 v176, v[116:119] offset:17408
	s_waitcnt lgkmcnt(13)
	ds_write_b128 v177, v[120:123] offset:34816
	s_waitcnt lgkmcnt(13)
	ds_write_b128 v178, v[124:127]
	s_waitcnt lgkmcnt(13)
	ds_write_b128 v178, v[132:135] offset:17408
	s_waitcnt lgkmcnt(13)
	ds_write_b128 v179, v[136:139] offset:34816
	s_waitcnt lgkmcnt(13)
	ds_write_b128 v180, v[140:143]
	s_waitcnt lgkmcnt(13)
	ds_write_b128 v180, v[144:147] offset:17408
	s_waitcnt lgkmcnt(13)
	ds_write_b128 v181, v[148:151] offset:34816
	s_waitcnt lgkmcnt(13)
	ds_write_b128 v182, v[152:155]
	s_waitcnt lgkmcnt(13)
	ds_write_b128 v182, v[156:159] offset:17408
	s_waitcnt lgkmcnt(13)
	ds_write_b128 v183, v[160:163] offset:34816
	s_waitcnt lgkmcnt(13)
	ds_write_b128 v202, v[164:167] offset:53248
	s_waitcnt lgkmcnt(13)
	ds_write_b128 v203, v[168:171] offset:53248
	s_waitcnt lgkmcnt(0)
	s_barrier
	s_cbranch_vccz .LBB0_232
	s_nop 0
	s_nop 0
	s_nop 0
	s_mov_b32 s52, 0x6600000
	s_andn2_b64 vcc, exec, s[60:61]
	s_cbranch_vccnz .LBB0_235
	s_movk_i32 s0, 0x1000
	v_add_co_u32_e32 v2, vcc, s0, v172
	s_movk_i32 s0, 0x2000
	s_nop 0
	v_addc_co_u32_e32 v3, vcc, 0, v173, vcc
	v_add_co_u32_e32 v4, vcc, s0, v172
	s_movk_i32 s0, 0x3000
	s_nop 0
	v_addc_co_u32_e32 v5, vcc, 0, v173, vcc
	global_store_dword v[172:173], v16, off
	global_store_dword v[172:173], v17, off offset:256
	global_store_dword v[172:173], v18, off offset:512
	global_store_dword v[172:173], v19, off offset:768
	global_store_dword v[172:173], v20, off offset:1024
	global_store_dword v[172:173], v21, off offset:1280
	global_store_dword v[172:173], v22, off offset:1536
	global_store_dword v[172:173], v23, off offset:1792
	global_store_dword v[172:173], v24, off offset:2048
	global_store_dword v[172:173], v25, off offset:2304
	global_store_dword v[172:173], v26, off offset:2560
	global_store_dword v[172:173], v27, off offset:2816
	global_store_dword v[172:173], v28, off offset:3072
	global_store_dword v[172:173], v29, off offset:3328
	global_store_dword v[172:173], v30, off offset:3584
	global_store_dword v[172:173], v31, off offset:3840
	global_store_dword v[4:5], v32, off offset:-4096
	global_store_dword v[2:3], v33, off offset:256
	global_store_dword v[2:3], v34, off offset:512
	global_store_dword v[2:3], v35, off offset:768
	global_store_dword v[2:3], v36, off offset:1024
	global_store_dword v[2:3], v37, off offset:1280
	global_store_dword v[2:3], v38, off offset:1536
	global_store_dword v[2:3], v39, off offset:1792
	global_store_dword v[2:3], v40, off offset:2048
	global_store_dword v[2:3], v41, off offset:2304
	global_store_dword v[2:3], v42, off offset:2560
	global_store_dword v[2:3], v43, off offset:2816
	global_store_dword v[2:3], v44, off offset:3072
	global_store_dword v[2:3], v45, off offset:3328
	global_store_dword v[2:3], v46, off offset:3584
	global_store_dword v[2:3], v47, off offset:3840
	global_store_dword v[4:5], v48, off
	global_store_dword v[4:5], v49, off offset:256
	global_store_dword v[4:5], v50, off offset:512
	global_store_dword v[4:5], v51, off offset:768
	global_store_dword v[4:5], v52, off offset:1024
	global_store_dword v[4:5], v53, off offset:1280
	global_store_dword v[4:5], v54, off offset:1536
	global_store_dword v[4:5], v55, off offset:1792
	global_store_dword v[4:5], v56, off offset:2048
	global_store_dword v[4:5], v57, off offset:2304
	global_store_dword v[4:5], v58, off offset:2560
	global_store_dword v[4:5], v59, off offset:2816
	global_store_dword v[4:5], v60, off offset:3072
	global_store_dword v[4:5], v61, off offset:3328
	global_store_dword v[4:5], v62, off offset:3584
	global_store_dword v[4:5], v63, off offset:3840
	v_add_co_u32_e32 v2, vcc, s0, v172
	s_nop 1
	v_addc_co_u32_e32 v3, vcc, 0, v173, vcc
	global_store_dword v[2:3], v64, off
	global_store_dword v[2:3], v65, off offset:256
	global_store_dword v[2:3], v66, off offset:512
	global_store_dword v[2:3], v67, off offset:768
	global_store_dword v[2:3], v68, off offset:1024
	global_store_dword v[2:3], v69, off offset:1280
	global_store_dword v[2:3], v70, off offset:1536
	global_store_dword v[2:3], v71, off offset:1792
	global_store_dword v[2:3], v72, off offset:2048
	global_store_dword v[2:3], v73, off offset:2304
	global_store_dword v[2:3], v74, off offset:2560
	global_store_dword v[2:3], v75, off offset:2816
	global_store_dword v[2:3], v76, off offset:3072
	global_store_dword v[2:3], v77, off offset:3328
	global_store_dword v[2:3], v78, off offset:3584
	global_store_dword v[2:3], v79, off offset:3840
